# v22 + attention: per-sub-tile accumulator splat of -m done with v_mov_b64 pairs (18 instead of 32 VALU)
# baseline (speedup 1.0000x reference)
; #define LAS __attribute__((address_space(3)))
; #define MFMA32(a, b, c) __builtin_amdgcn_mfma_f32_32x32x16_bf16((a), (b), (c), 0, 0, 0)
; __device__ __forceinline__ void attn_phase(LAS unsigned char* lds, const bf16_t* QKVZ, bf16_t* AO, const float* sink) {
;     ...
;                 if ((mode == 1 && sub < qh) || (mode == 2 && sub > qh)) continue;
;                 f32x16 S[2][2];
; #pragma unroll
;                 for (int kt = 0; kt < 2; ++kt)
; #pragma unroll
;                     for (int qt = 0; qt < 2; ++qt)
; #pragma unroll
;                         for (int i = 0; i < 16; ++i) S[kt][qt][i] = -m_[qt];
; #pragma unroll
;                 for (int kt = 0; kt < 2; ++kt)
; #pragma unroll
;                     for (int ks = 0; ks < 4; ++ks) {
;                         const bf16x8 Kf = *(const LAS bf16x8*)(Ks + (64 * sub + 32 * kt + ql) * KS_PITCH + (16 * ks + 8 * hh) * 2);
;                         S[kt][0] = MFMA32(Kf, Qf[0][ks], S[kt][0]);
;                         S[kt][1] = MFMA32(Kf, Qf[1][ks], S[kt][1]);
;                     }
;                 if (mode) {
; #pragma unroll
;                     for (int kt = 0; kt < 2; ++kt)
; #pragma unroll
;                         for (int qt = 0; qt < 2; ++qt)
; #pragma unroll
;                             for (int i = 0; i < 16; ++i) {
;                                 const int j = 64 * sub + 32 * kt + 8 * (i >> 2) + 4 * hh + (i & 3), iq = 64 * qh + 32 * qt + ql;
;                                 const bool valid = (mode == 1) ? (j >= iq) : (j <= iq);
;                                 S[kt][qt][i] = valid ? S[kt][qt][i] : -1e30f;
;                             }
.LBB0_311:
	s_cmp_lt_i32 s75, s58
	s_cselect_b64 s[0:1], -1, 0
	s_and_b64 s[0:1], s[2:3], s[0:1]
	s_cmp_gt_i32 s75, s58
	s_cselect_b64 s[76:77], -1, 0
	s_and_b64 s[76:77], s[48:49], s[76:77]
	s_or_b64 s[0:1], s[0:1], s[76:77]
	s_and_b64 vcc, exec, s[0:1]
	s_cbranch_vccnz .LBB0_310
	s_lshl_b32 s0, s75, 6
	v_or_b32_e32 v6, s0, v193
	v_mad_u32_u24 v6, v6, s61, v10
	ds_read_b128 v[12:15], v6
	ds_read_b128 v[228:231], v6 offset:32
	v_xor_b32_e32 v96, 0x80000000, v9
	v_xor_b32_e32 v80, 0x80000000, v7
	v_mov_b32_e32 v97, v96
	v_mov_b32_e32 v81, v80
	v_mov_b64_e32 v[98:99], v[96:97]
	v_mov_b64_e32 v[100:101], v[96:97]
	v_mov_b64_e32 v[102:103], v[96:97]
	v_mov_b64_e32 v[104:105], v[96:97]
	v_mov_b64_e32 v[106:107], v[96:97]
	v_mov_b64_e32 v[108:109], v[96:97]
	v_mov_b64_e32 v[110:111], v[96:97]
	v_mov_b64_e32 v[82:83], v[80:81]
	v_mov_b64_e32 v[84:85], v[80:81]
	v_mov_b64_e32 v[86:87], v[80:81]
	v_mov_b64_e32 v[88:89], v[80:81]
	v_mov_b64_e32 v[90:91], v[80:81]
	v_mov_b64_e32 v[92:93], v[80:81]
	v_mov_b64_e32 v[94:95], v[80:81]
	s_waitcnt lgkmcnt(1)
	v_mfma_f32_32x32x16_bf16 v[128:143], v[12:15], v[144:147], v[96:111]
	s_andn2_b64 vcc, exec, s[50:51]
	v_mfma_f32_32x32x16_bf16 v[112:127], v[12:15], v[160:163], v[80:95]
	s_waitcnt lgkmcnt(0)
	v_mfma_f32_32x32x16_bf16 v[128:143], v[228:231], v[148:151], v[128:143]
	v_mfma_f32_32x32x16_bf16 v[112:127], v[228:231], v[164:167], v[112:127]
	ds_read_b128 v[12:15], v6 offset:64
	ds_read_b128 v[228:231], v6 offset:96
	s_waitcnt lgkmcnt(1)
	v_mfma_f32_32x32x16_bf16 v[128:143], v[12:15], v[152:155], v[128:143]
	v_mfma_f32_32x32x16_bf16 v[112:127], v[12:15], v[168:171], v[112:127]
	s_waitcnt lgkmcnt(0)
	v_mfma_f32_32x32x16_bf16 v[128:143], v[228:231], v[156:159], v[128:143]
	v_mfma_f32_32x32x16_bf16 v[112:127], v[228:231], v[172:175], v[112:127]
	ds_read_b128 v[12:15], v6 offset:4608
	ds_read_b128 v[228:231], v6 offset:4640
	s_waitcnt lgkmcnt(1)
	v_mfma_f32_32x32x16_bf16 v[96:111], v[12:15], v[144:147], v[96:111]
	v_mfma_f32_32x32x16_bf16 v[80:95], v[12:15], v[160:163], v[80:95]
	s_waitcnt lgkmcnt(0)
	v_mfma_f32_32x32x16_bf16 v[96:111], v[228:231], v[148:151], v[96:111]
	v_mfma_f32_32x32x16_bf16 v[80:95], v[228:231], v[164:167], v[80:95]
	ds_read_b128 v[12:15], v6 offset:4672
	ds_read_b128 v[228:231], v6 offset:4704
	s_waitcnt lgkmcnt(1)
	v_mfma_f32_32x32x16_bf16 v[96:111], v[12:15], v[152:155], v[96:111]
	v_mfma_f32_32x32x16_bf16 v[80:95], v[12:15], v[168:171], v[80:95]
	s_waitcnt lgkmcnt(0)
	v_mfma_f32_32x32x16_bf16 v[96:111], v[228:231], v[156:159], v[96:111]
	v_mfma_f32_32x32x16_bf16 v[80:95], v[228:231], v[172:175], v[80:95]
	s_cbranch_vccnz .LBB0_314
	s_cmp_lg_u32 s75, s58
	s_cbranch_scc1 .LBB0_314
	v_or_b32_e32 v6, s0, v214
	v_sub_u32_e32 v8, v215, v6
	s_and_b64 vcc, exec, s[2:3]
	s_nop 4
	s_cbranch_vccz .Lattn_mask_m2
	v_cmp_ge_i32_e64 s[0:1], 0, v8
	v_cmp_ge_i32_e64 s[96:97], 1, v8
	v_cmp_ge_i32_e64 s[98:99], 2, v8
	v_cmp_ge_i32_e64 s[100:101], 3, v8
	v_cndmask_b32_e64 v128, v226, v128, s[0:1]
	v_cndmask_b32_e64 v80, v226, v80, s[0:1]
	v_cndmask_b32_e64 v129, v226, v129, s[96:97]
	v_cndmask_b32_e64 v81, v226, v81, s[96:97]
	v_cndmask_b32_e64 v130, v226, v130, s[98:99]
	v_cndmask_b32_e64 v82, v226, v82, s[98:99]
	v_cndmask_b32_e64 v131, v226, v131, s[100:101]
	v_cndmask_b32_e64 v83, v226, v83, s[100:101]
	v_cmp_ge_i32_e64 s[0:1], 8, v8
	v_cmp_ge_i32_e64 s[96:97], 9, v8
	v_cmp_ge_i32_e64 s[98:99], 10, v8
	v_cmp_ge_i32_e64 s[100:101], 11, v8
	v_cndmask_b32_e64 v132, v226, v132, s[0:1]
	v_cndmask_b32_e64 v84, v226, v84, s[0:1]
	v_cndmask_b32_e64 v133, v226, v133, s[96:97]
	v_cndmask_b32_e64 v85, v226, v85, s[96:97]
	v_cndmask_b32_e64 v134, v226, v134, s[98:99]
	v_cndmask_b32_e64 v86, v226, v86, s[98:99]
	v_cndmask_b32_e64 v135, v226, v135, s[100:101]
	v_cndmask_b32_e64 v87, v226, v87, s[100:101]
	v_cmp_ge_i32_e64 s[0:1], 16, v8
	v_cmp_ge_i32_e64 s[96:97], 17, v8
	v_cmp_ge_i32_e64 s[98:99], 18, v8
	v_cmp_ge_i32_e64 s[100:101], 19, v8
	v_cndmask_b32_e64 v136, v226, v136, s[0:1]
	v_cndmask_b32_e64 v88, v226, v88, s[0:1]
	v_cndmask_b32_e64 v137, v226, v137, s[96:97]
	v_cndmask_b32_e64 v89, v226, v89, s[96:97]
	v_cndmask_b32_e64 v138, v226, v138, s[98:99]
	v_cndmask_b32_e64 v90, v226, v90, s[98:99]
	v_cndmask_b32_e64 v139, v226, v139, s[100:101]
	v_cndmask_b32_e64 v91, v226, v91, s[100:101]
	v_cmp_ge_i32_e64 s[0:1], 24, v8
	v_cmp_ge_i32_e64 s[96:97], 25, v8
	v_cmp_ge_i32_e64 s[98:99], 26, v8
	v_cmp_ge_i32_e64 s[100:101], 27, v8
	v_cndmask_b32_e64 v140, v226, v140, s[0:1]
	v_cndmask_b32_e64 v92, v226, v92, s[0:1]
	v_cndmask_b32_e64 v141, v226, v141, s[96:97]
	v_cndmask_b32_e64 v93, v226, v93, s[96:97]
	v_cndmask_b32_e64 v142, v226, v142, s[98:99]
	v_cndmask_b32_e64 v94, v226, v94, s[98:99]
	v_cndmask_b32_e64 v143, v226, v143, s[100:101]
	v_cndmask_b32_e64 v95, v226, v95, s[100:101]
	v_mov_b32_e32 v112, v226
	v_mov_b32_e32 v113, v226
	v_mov_b32_e32 v114, v226
	v_mov_b32_e32 v115, v226
	v_mov_b32_e32 v116, v226
	v_mov_b32_e32 v117, v226
	v_mov_b32_e32 v118, v226
	v_mov_b32_e32 v119, v226
	v_mov_b32_e32 v120, v226
	v_mov_b32_e32 v121, v226
	v_mov_b32_e32 v122, v226
	v_mov_b32_e32 v123, v226
	v_mov_b32_e32 v124, v226
	v_mov_b32_e32 v125, v226
	v_mov_b32_e32 v126, v226
	v_mov_b32_e32 v127, v226
	s_branch .LBB0_314
